# one static s_setprio 2 for the side-transposes waves (latency-chained) during the H stage, on top of fold v62
# speedup vs baseline: 1.0047x; 1.0047x over previous
; #define LAS __attribute__((address_space(3)))
; __device__ __forceinline__ int fresh_tid() { int t = threadIdx.x; asm volatile("" : "+v"(t)); return t; }
; __device__ __forceinline__ void side_transposes(const P& p, LAS unsigned char* lds, int sw, int lane, int G) {
;     unsigned char* ws = p.ws;
;     LAS float* scr = (LAS float*)(lds + sw * 16640);
;     bf16_t* BTO = (bf16_t*)(ws + O_BTO); bf16_t* BTU = (bf16_t*)(ws + O_BTU); bf16_t* BTD = (bf16_t*)(ws + O_BTD);
;     constexpr int I_O = 32 * 32, I_U = 32 * 128, I_D = 128 * 32;
;     for (int it = sw * G + blockIdx.x; it < I_O + I_U + I_D; it += 4 * G) {
;         int r = it;
; __global__ void __launch_bounds__(NTHR) fwd_megakernel(P p) {
;     ...
;         { const int t0 = fresh_tid(); const int w = __builtin_amdgcn_readfirstlane(t0 >> 6);
;           __syncthreads();
;           if (w < 4) { for (int wi = w * G + blockIdx.x; wi < 1024; wi += G * 4) attn_sample_item(p, wi, t0 & 63); }
;           else side_transposes(p, lds, w - 4, t0 & 63, G); }
.Lp2_hstage:
	s_nop 0
	v_readfirstlane_b32 s0, v42
	s_ashr_i32 s3, s0, 6
	s_cmp_gt_i32 s3, 3
	s_mov_b64 s[0:1], -1
	s_barrier
	s_cbranch_scc0 .LBB0_453
	s_setprio 2
	s_add_i32 s0, s3, -4
	s_mul_i32 s1, s0, s34
	s_add_i32 s16, s1, s2
	v_writelane_b32 v255, s3, 21
	s_cmpk_gt_i32 s16, 0x23ff
	s_cbranch_scc1 .LBB0_452
	v_lshlrev_b32_e32 v0, 3, v42
	v_and_b32_e32 v0, 56, v0
	s_mulk_i32 s0, 0x4100
	v_mov_b32_e32 v1, 0
	v_mul_u32_u24_e32 v4, 0x104, v0
	v_lshlrev_b32_e32 v0, 1, v0
	s_add_i32 s3, s0, 0
	v_bfe_u32 v44, v42, 3, 3
	v_lshl_add_u64 v[6:7], s[70:71], 0, v[0:1]
	s_mov_b64 s[0:1], 0x6126400
	v_and_b32_e32 v8, 63, v42
	v_lshl_add_u64 v[2:3], v[6:7], 0, s[0:1]
	v_lshlrev_b32_e32 v0, 2, v44
	s_mov_b64 s[0:1], 0x4126400
	s_lshl_b32 s17, s34, 2
	v_lshl_add_u32 v43, v8, 2, s3
	v_add3_u32 v45, s3, v4, v0
	v_lshl_add_u64 v[4:5], v[6:7], 0, s[0:1]
	s_mov_b64 s[0:1], 0x3926400
	s_cmp_lg_u64 s[44:45], 0
	v_or_b32_e32 v46, 8, v44
	v_or_b32_e32 v47, 16, v44
	v_or_b32_e32 v48, 24, v44
	v_or_b32_e32 v49, 32, v44
	v_or_b32_e32 v50, 40, v44
	v_or_b32_e32 v51, 48, v44
	v_or_b32_e32 v52, 56, v44
	v_lshl_add_u64 v[6:7], v[6:7], 0, s[0:1]
	s_cselect_b64 s[4:5], -1, 0
	s_lshl_b32 s18, s16, 6
	s_lshl_b32 s19, s34, 8
	s_lshl_b32 s20, s16, 1
	s_movk_i32 s93, 0x2000
	s_mov_b32 s28, 0x8000
	s_mov_b32 s52, 0x10000
	s_mov_b32 s64, 0x18000
	s_mov_b32 s79, 0x20000
	s_mov_b32 s83, 0x28000
	s_mov_b32 s87, 0x30000
	s_mov_b32 s91, 0x38000
	s_mov_b32 s94, 0x3e000
	s_mov_b32 s95, 0x40000
	s_mov_b32 s96, 0x42000
	s_mov_b32 s97, 0x44000
	s_mov_b32 s23, 0x46000
	s_mov_b32 s26, 0x48000
	s_mov_b32 s27, 0x4a000
	s_mov_b32 s33, 0x4c000
	s_mov_b32 s76, 0x4e000
	s_mov_b32 s77, 0x50000
	s_mov_b32 s3, 0x52000
	s_mov_b32 s21, 0x54000
	s_mov_b32 s24, 0x56000
	s_mov_b32 s25, 0x58000
	s_mov_b32 s29, 0x5a000
	s_mov_b32 s30, 0x5c000
	s_mov_b32 s31, 0x5e000
	s_mov_b32 s53, 0x60000
	s_mov_b32 s62, 0x62000
	s_mov_b32 s63, 0x64000
	s_mov_b32 s65, 0x66000
	s_mov_b32 s75, 0x68000
	s_mov_b32 s78, 0x6a000
	s_mov_b32 s80, 0x6c000
	s_mov_b32 s81, 0x6e000
	s_mov_b32 s82, 0x70000
	s_mov_b32 s84, 0x72000
	s_mov_b32 s85, 0x74000
	s_mov_b32 s86, 0x76000
	s_mov_b32 s88, 0x78000
	s_mov_b32 s89, 0x7a000
	s_mov_b32 s90, 0x7c000
	s_mov_b32 s92, 0x7e000
	v_lshlrev_b32_e32 v0, 2, v8
	v_add_u32_e32 v53, 0x400, v43
	v_add_u32_e32 v54, 0x800, v43
	v_add_u32_e32 v55, 0xc00, v43
	v_add_u32_e32 v56, 0x1000, v43
	v_add_u32_e32 v57, 0x1400, v43
	v_add_u32_e32 v58, 0x1800, v43
	v_add_u32_e32 v59, 0x1c00, v43
	v_add_u32_e32 v60, 0x2000, v43
	v_add_u32_e32 v61, 0x2400, v43
	v_add_u32_e32 v62, 0x2800, v43
	v_add_u32_e32 v63, 0x2c00, v43
	v_add_u32_e32 v64, 0x3000, v43
	v_add_u32_e32 v65, 0x3400, v43
	v_add_u32_e32 v66, 0x3800, v43
	v_add_u32_e32 v67, 0x3c00, v43
	v_add_u32_e32 v68, 0x400, v45
	s_mov_b32 s7, 0
	s_branch .LBB0_380

; #define LAS __attribute__((address_space(3)))
; __device__ __forceinline__ void side_transposes(const P& p, LAS unsigned char* lds, int sw, int lane, int G) {
;     unsigned char* ws = p.ws;
;     LAS float* scr = (LAS float*)(lds + sw * 16640);
;     bf16_t* BTO = (bf16_t*)(ws + O_BTO); bf16_t* BTU = (bf16_t*)(ws + O_BTU); bf16_t* BTD = (bf16_t*)(ws + O_BTD);
;     constexpr int I_O = 32 * 32, I_U = 32 * 128, I_D = 128 * 32;
;     for (int it = sw * G + blockIdx.x; it < I_O + I_U + I_D; it += 4 * G) {
;         int r = it;
;         if (r < I_O) { const int kb = r / 32, nb = r % 32; tr_item(p.w_out, DM, kb * 64, nb * 64, 64, nullptr, BTO, DM, nb * 64, scr, lane); continue; }
;         r -= I_O;
;         if (r < I_U) { const int kb = r / 128, nb = r % 128; tr_item(p.w_up, DFF, kb * 64, nb * 64, 64, p.ffn_norm_w, BTU, DM, nb * 64, scr, lane); continue; }
;         r -= I_U;
;         { const int kb = r / 32, nb = r % 32; tr_item(p.w_down, DM, kb * 64, nb * 64, 64, nullptr, BTD, DFF, nb * 64, scr, lane); }
;     }
; }
.LBB0_452:
	s_setprio 0
	v_readlane_b32 s96, v255, 7
	v_readlane_b32 s74, v255, 1
	s_mov_b64 s[0:1], 0
	v_readlane_b32 s94, v255, 5
	v_readlane_b32 s95, v255, 6
	v_readlane_b32 s97, v255, 8
	v_readlane_b32 s75, v255, 2
	v_readlane_b32 s3, v255, 21
